# pp_v19 + RC1 stale S0b/S0c vmcnt waits removed (they only waited for the previous unit's store acks; loads are complete at the unit head)
# speedup vs baseline: 1.0023x; 1.0023x over previous
.Lrc_hw:
	s_waitcnt vmcnt(4)
	v_mov_b64_e32 v[30:31], v[200:201]
	v_mov_b64_e32 v[32:33], v[202:203]
	v_mov_b64_e32 v[26:27], v[204:205]
	v_mov_b64_e32 v[28:29], v[206:207]
	v_mov_b64_e32 v[14:15], v[208:209]
	v_mov_b64_e32 v[16:17], v[210:211]
	v_mov_b64_e32 v[38:39], v[212:213]
	v_mov_b64_e32 v[40:41], v[214:215]
	v_mov_b64_e32 v[34:35], v[216:217]
	v_mov_b64_e32 v[36:37], v[218:219]
	v_mov_b64_e32 v[18:19], v[220:221]
	v_mov_b64_e32 v[20:21], v[222:223]
	v_mov_b64_e32 v[42:43], v[224:225]
	v_mov_b64_e32 v[44:45], v[226:227]
	s_lshl_b32 s0, s46, 8
	s_and_b32 s0, s0, 0x100
	s_add_i32 s47, s0, 0
	s_add_i32 s47, s47, 0x22500
	s_add_i32 s2, s47, s65
	v_add_f32_dpp v200, v6, v6 row_shr:1 row_mask:0xf bank_mask:0xf bound_ctrl:1
	v_add_f32_dpp v201, v7, v7 row_shr:1 row_mask:0xf bank_mask:0xf bound_ctrl:1
	v_add_f32_dpp v202, v8, v8 row_shr:1 row_mask:0xf bank_mask:0xf bound_ctrl:1
	v_add_f32_dpp v203, v9, v9 row_shr:1 row_mask:0xf bank_mask:0xf bound_ctrl:1
	v_add_f32_dpp v204, v2, v2 row_shr:1 row_mask:0xf bank_mask:0xf bound_ctrl:1
	v_add_f32_dpp v205, v3, v3 row_shr:1 row_mask:0xf bank_mask:0xf bound_ctrl:1
	v_add_f32_dpp v206, v4, v4 row_shr:1 row_mask:0xf bank_mask:0xf bound_ctrl:1
	v_add_f32_dpp v207, v5, v5 row_shr:1 row_mask:0xf bank_mask:0xf bound_ctrl:1
	v_add_f32_dpp v200, v200, v200 row_shr:2 row_mask:0xf bank_mask:0xf bound_ctrl:1
	v_add_f32_dpp v201, v201, v201 row_shr:2 row_mask:0xf bank_mask:0xf bound_ctrl:1
	v_add_f32_dpp v202, v202, v202 row_shr:2 row_mask:0xf bank_mask:0xf bound_ctrl:1
	v_add_f32_dpp v203, v203, v203 row_shr:2 row_mask:0xf bank_mask:0xf bound_ctrl:1
	v_add_f32_dpp v204, v204, v204 row_shr:2 row_mask:0xf bank_mask:0xf bound_ctrl:1
	v_add_f32_dpp v205, v205, v205 row_shr:2 row_mask:0xf bank_mask:0xf bound_ctrl:1
	v_add_f32_dpp v206, v206, v206 row_shr:2 row_mask:0xf bank_mask:0xf bound_ctrl:1
	v_add_f32_dpp v207, v207, v207 row_shr:2 row_mask:0xf bank_mask:0xf bound_ctrl:1
	v_add_f32_dpp v200, v200, v200 row_shr:4 row_mask:0xf bank_mask:0xf bound_ctrl:1
	v_add_f32_dpp v201, v201, v201 row_shr:4 row_mask:0xf bank_mask:0xf bound_ctrl:1
	v_add_f32_dpp v202, v202, v202 row_shr:4 row_mask:0xf bank_mask:0xf bound_ctrl:1
	v_add_f32_dpp v203, v203, v203 row_shr:4 row_mask:0xf bank_mask:0xf bound_ctrl:1
	v_add_f32_dpp v204, v204, v204 row_shr:4 row_mask:0xf bank_mask:0xf bound_ctrl:1
	v_add_f32_dpp v205, v205, v205 row_shr:4 row_mask:0xf bank_mask:0xf bound_ctrl:1
	v_add_f32_dpp v206, v206, v206 row_shr:4 row_mask:0xf bank_mask:0xf bound_ctrl:1
	v_add_f32_dpp v207, v207, v207 row_shr:4 row_mask:0xf bank_mask:0xf bound_ctrl:1
	v_add_f32_dpp v200, v200, v200 row_shr:8 row_mask:0xf bank_mask:0xf bound_ctrl:1
	v_add_f32_dpp v201, v201, v201 row_shr:8 row_mask:0xf bank_mask:0xf bound_ctrl:1
	v_add_f32_dpp v202, v202, v202 row_shr:8 row_mask:0xf bank_mask:0xf bound_ctrl:1
	v_add_f32_dpp v203, v203, v203 row_shr:8 row_mask:0xf bank_mask:0xf bound_ctrl:1
	v_add_f32_dpp v204, v204, v204 row_shr:8 row_mask:0xf bank_mask:0xf bound_ctrl:1
	v_add_f32_dpp v205, v205, v205 row_shr:8 row_mask:0xf bank_mask:0xf bound_ctrl:1
	v_add_f32_dpp v206, v206, v206 row_shr:8 row_mask:0xf bank_mask:0xf bound_ctrl:1
	v_add_f32_dpp v207, v207, v207 row_shr:8 row_mask:0xf bank_mask:0xf bound_ctrl:1
	v_mov_b32_e32 v208, v89
	v_mov_b32_e32 v209, v89
	v_mov_b32_e32 v210, v89
	v_mov_b32_e32 v211, v89
	v_mov_b32_e32 v212, v89
	v_mov_b32_e32 v213, v89
	v_mov_b32_e32 v214, v89
	v_mov_b32_e32 v215, v89
	v_mov_b32_dpp v208, v200 row_bcast:15 row_mask:0xa bank_mask:0xf
	v_mov_b32_dpp v209, v201 row_bcast:15 row_mask:0xa bank_mask:0xf
	v_mov_b32_dpp v210, v202 row_bcast:15 row_mask:0xa bank_mask:0xf
	v_mov_b32_dpp v211, v203 row_bcast:15 row_mask:0xa bank_mask:0xf
	v_mov_b32_dpp v212, v204 row_bcast:15 row_mask:0xa bank_mask:0xf
	v_mov_b32_dpp v213, v205 row_bcast:15 row_mask:0xa bank_mask:0xf
	v_mov_b32_dpp v214, v206 row_bcast:15 row_mask:0xa bank_mask:0xf
	v_mov_b32_dpp v215, v207 row_bcast:15 row_mask:0xa bank_mask:0xf
	v_add_f32_e32 v200, v200, v208
	v_add_f32_e32 v201, v201, v209
	v_add_f32_e32 v202, v202, v210
	v_add_f32_e32 v203, v203, v211
	v_add_f32_e32 v204, v204, v212
	v_add_f32_e32 v205, v205, v213
	v_add_f32_e32 v206, v206, v214
	v_add_f32_e32 v207, v207, v215
	v_mov_b32_e32 v208, v89
	v_mov_b32_e32 v209, v89
	v_mov_b32_e32 v210, v89
	v_mov_b32_e32 v211, v89
	v_mov_b32_e32 v212, v89
	v_mov_b32_e32 v213, v89
	v_mov_b32_e32 v214, v89
	v_mov_b32_e32 v215, v89
	v_mov_b32_dpp v208, v200 row_bcast:31 row_mask:0xc bank_mask:0xf
	v_mov_b32_dpp v209, v201 row_bcast:31 row_mask:0xc bank_mask:0xf
	v_mov_b32_dpp v210, v202 row_bcast:31 row_mask:0xc bank_mask:0xf
	v_mov_b32_dpp v211, v203 row_bcast:31 row_mask:0xc bank_mask:0xf
	v_mov_b32_dpp v212, v204 row_bcast:31 row_mask:0xc bank_mask:0xf
	v_mov_b32_dpp v213, v205 row_bcast:31 row_mask:0xc bank_mask:0xf
	v_mov_b32_dpp v214, v206 row_bcast:31 row_mask:0xc bank_mask:0xf
	v_mov_b32_dpp v215, v207 row_bcast:31 row_mask:0xc bank_mask:0xf
	v_add_f32_e32 v200, v200, v208
	v_add_f32_e32 v201, v201, v209
	v_add_f32_e32 v202, v202, v210
	v_add_f32_e32 v203, v203, v211
	v_add_f32_e32 v204, v204, v212
	v_add_f32_e32 v205, v205, v213
	v_add_f32_e32 v206, v206, v214
	v_add_f32_e32 v207, v207, v215
	ds_write_b32 v111, v200
	ds_write_b32 v111, v201 offset:4
	ds_write_b32 v111, v202 offset:8
	ds_write_b32 v111, v203 offset:12
	ds_write_b32 v111, v204 offset:16
	ds_write_b32 v111, v205 offset:20
	ds_write_b32 v111, v206 offset:24
	ds_write_b32 v111, v207 offset:28
	s_and_saveexec_b64 s[0:1], s[44:45]
	v_mov_b32_e32 v22, s2
	ds_write_b32 v22, v200
	ds_write_b32 v22, v201 offset:4
	ds_write_b32 v22, v202 offset:8
	ds_write_b32 v22, v203 offset:12
	ds_write_b32 v22, v204 offset:16
	ds_write_b32 v22, v205 offset:20
	ds_write_b32 v22, v206 offset:24
	ds_write_b32 v22, v207 offset:28
	s_or_b64 exec, exec, s[0:1]
	v_and_b32_e32 v195, 0xffff0000, v30
	v_lshlrev_b32_e32 v194, 16, v30
	v_and_b32_e32 v199, 0xffff0000, v38
	v_lshlrev_b32_e32 v198, 16, v38
	s_waitcnt lgkmcnt(0)
	s_barrier
	ds_read_b128 v[82:85], v167
	ds_read_b128 v[54:57], v167 offset:16
	ds_read_b128 v[70:73], v167 offset:32
	ds_read_b128 v[50:53], v167 offset:48
	ds_read_b128 v[22:25], v167 offset:64
	ds_read_b128 v[78:81], v167 offset:96
	ds_read_b128 v[46:49], v167 offset:112
	ds_read_b128 v[74:77], v167 offset:128
	ds_read_b128 v[62:65], v167 offset:144
	ds_read_b128 v[66:69], v167 offset:160
	ds_read_b128 v[58:61], v167 offset:176
	v_pk_add_f32 v[198:199], v[198:199], v[194:195] neg_lo:[0,1] neg_hi:[0,1]
	v_and_b32_e32 v197, 0xffff0000, v26
	v_lshlrev_b32_e32 v196, 16, v26
	s_waitcnt lgkmcnt(10)
	v_pk_fma_f32 v[82:83], v[198:199], v[82:83], v[194:195]
	v_and_b32_e32 v195, 0xffff0000, v34
	v_lshlrev_b32_e32 v194, 16, v34
	s_cmp_eq_u32 s46, 15
	s_cbranch_scc1 .Lrc_nopf
	s_add_i32 s100, s46, 1
	s_lshl_b32 s100, s100, 2
	s_or_b32 s100, s84, s100
	s_lshl_b32 s100, s100, 6
	s_or_b32 s100, s52, s100
	s_mov_b32 s101, s53
	v_lshl_add_u64 v[228:229], s[100:101], 0, v[90:91]
	v_mad_u64_u32 v[230:231], s[100:101], v228, s64, v[94:95]
	v_mad_i32_i24 v231, v229, s64, v231
	v_lshlrev_b64 v[228:229], 10, v[228:229]
	v_lshl_add_u64 v[232:233], v[96:97], 0, v[228:229]
	global_load_dwordx4 v[200:203], v[230:231], off
	global_load_dwordx4 v[204:207], v[230:231], off offset:1024
	global_load_dwordx4 v[208:211], v[230:231], off offset:2048
	global_load_dwordx4 v[212:215], v[230:231], off offset:-3648
	global_load_dwordx4 v[216:219], v[230:231], off offset:-2624
	global_load_dwordx4 v[220:223], v[230:231], off offset:-1600
	global_load_dwordx4 v[224:227], v[232:233], off
	s_add_i32 s100, s54, 0x100
	s_mov_b32 s101, s55
	v_lshl_add_u64 v[2:3], v[92:93], 0, s[100:101]
	v_lshlrev_b64 v[2:3], 11, v[2:3]
	v_lshl_add_u64 v[6:7], v[98:99], 0, v[2:3]
	global_load_dwordx4 v[2:5], v[6:7], off offset:16
	s_nop 0
	global_load_dwordx4 v[6:9], v[6:7], off
